# grid barrier v3: arrival per physical XCC (HW_REG_XCC_ID, census at start), only the last local arriver issues the XCD-wide L2 write-back; ready-word start handshake
# speedup vs baseline: 1.0343x; 1.0070x over previous
_Z14fwd_megakernel6Params:
	s_load_dwordx4 s[68:71], s[0:1], 0x80
	s_load_dwordx16 s[36:51], s[0:1], 0x0
	s_load_dwordx2 s[34:35], s[0:1], 0x90
	s_load_dwordx16 s[16:31], s[0:1], 0x40
	s_mov_b32 s12, s2
	s_waitcnt lgkmcnt(0)
	s_add_u32 s14, s70, 0x1f7a0000
	v_and_b32_e32 v1, 0x3ff, v0
	s_addc_u32 s15, s71, 0
	v_writelane_b32 v244, s16, 0
	s_sub_i32 s2, s35, s34
	s_cmp_lt_i32 s2, 2
	v_writelane_b32 v244, s17, 1
	v_writelane_b32 v244, s18, 2
	v_writelane_b32 v244, s19, 3
	v_writelane_b32 v244, s20, 4
	v_writelane_b32 v244, s21, 5
	v_writelane_b32 v244, s22, 6
	v_writelane_b32 v244, s23, 7
	v_writelane_b32 v244, s24, 8
	v_writelane_b32 v244, s25, 9
	v_writelane_b32 v244, s26, 10
	v_writelane_b32 v244, s27, 11
	v_writelane_b32 v244, s28, 12
	v_writelane_b32 v244, s29, 13
	v_writelane_b32 v244, s30, 14
	v_readfirstlane_b32 s10, v1
	v_writelane_b32 v244, s31, 15
	s_cbranch_scc1 .LBB0_14
	v_or_b32_e32 v2, s12, v1
	v_cmp_eq_u32_e32 vcc, 0, v2
	s_and_saveexec_b64 s[2:3], vcc
	s_cbranch_execz .LBB0_3
	v_mov_b32_e32 v2, 0
	global_store_dword v2, v2, s[14:15] sc1
	global_store_dword v2, v2, s[68:69] sc1
	global_store_dword v2, v2, s[68:69] offset:256 sc1
	global_store_dword v2, v2, s[68:69] offset:512 sc1
	global_store_dword v2, v2, s[68:69] offset:768 sc1
	global_store_dword v2, v2, s[68:69] offset:1024 sc1
	global_store_dword v2, v2, s[68:69] offset:1280 sc1
	global_store_dword v2, v2, s[68:69] offset:1536 sc1
	global_store_dword v2, v2, s[68:69] offset:1792 sc1
	v_mov_b32_e32 v3, 0x1000
	global_store_dword v3, v2, s[68:69] sc1
	global_store_dword v3, v2, s[68:69] offset:256 sc1
	global_store_dword v3, v2, s[68:69] offset:512 sc1
	global_store_dword v3, v2, s[68:69] offset:768 sc1
	global_store_dword v3, v2, s[68:69] offset:1024 sc1
	global_store_dword v3, v2, s[68:69] offset:1280 sc1
	global_store_dword v3, v2, s[68:69] offset:1536 sc1
	global_store_dword v3, v2, s[68:69] offset:1792 sc1
	s_waitcnt vmcnt(0)
	v_mov_b32_e32 v3, 0x13579bdf
	global_store_dword v2, v3, s[14:15] offset:64 sc1

.Lrdy_done:
	s_getreg_b32 s5, hwreg(HW_REG_XCC_ID, 0, 4)
	s_lshl_b32 s5, s5, 8
	s_add_u32 s5, s5, 0x1000
	v_mov_b32_e32 v0, s5
	v_mov_b32_e32 v2, 1
	global_atomic_add v0, v2, s[68:69]

.LBB0_62:
	s_or_b64 exec, exec, s[2:3]
	s_cmp_lt_i32 s35, 2
	s_cbranch_scc1 .LBB0_71
	s_waitcnt vmcnt(1)
	v_mbcnt_lo_u32_b32 v0, -1, 0
	v_mbcnt_hi_u32_b32 v0, -1, v0
	s_waitcnt vmcnt(0) lgkmcnt(0)
	s_waitcnt lgkmcnt(0)
	v_add_u32_e32 v0, s84, v0
	v_cmp_gt_u32_e32 vcc, 64, v0
	s_barrier
	s_and_saveexec_b64 s[0:1], vcc
	s_cbranch_execz .LBB0_70
	s_waitcnt vmcnt(0)
	s_waitcnt vmcnt(0)
	v_cmp_eq_u32_e32 vcc, 0, v0
	s_and_saveexec_b64 s[2:3], vcc
	s_cbranch_execz .LBB0_69
	v_mov_b32_e32 v0, 0x1000
.Lcen_spin:
	global_load_dword v2, v0, s[68:69] sc1
	global_load_dword v3, v0, s[68:69] offset:256 sc1
	global_load_dword v4, v0, s[68:69] offset:512 sc1
	global_load_dword v5, v0, s[68:69] offset:768 sc1
	global_load_dword v6, v0, s[68:69] offset:1024 sc1
	global_load_dword v7, v0, s[68:69] offset:1280 sc1
	global_load_dword v8, v0, s[68:69] offset:1536 sc1
	global_load_dword v9, v0, s[68:69] offset:1792 sc1
	s_waitcnt vmcnt(0)
	v_add_u32_e32 v1, v2, v3
	v_add_u32_e32 v1, v1, v4
	v_add_u32_e32 v1, v1, v5
	v_add_u32_e32 v1, v1, v6
	v_add_u32_e32 v1, v1, v7
	v_add_u32_e32 v1, v1, v8
	v_add_u32_e32 v1, v1, v9
	v_cmp_eq_u32_e32 vcc, s13, v1
	s_cbranch_vccnz .Lcen_done
	s_sleep 1
	s_branch .Lcen_spin
.Lcen_done:
	v_min_u32_e32 v2, 1, v2
	v_min_u32_e32 v3, 1, v3
	v_min_u32_e32 v4, 1, v4
	v_min_u32_e32 v5, 1, v5
	v_min_u32_e32 v6, 1, v6
	v_min_u32_e32 v7, 1, v7
	v_min_u32_e32 v8, 1, v8
	v_min_u32_e32 v9, 1, v9
	v_add_u32_e32 v1, v2, v3
	v_add_u32_e32 v1, v1, v4
	v_add_u32_e32 v1, v1, v5
	v_add_u32_e32 v1, v1, v6
	v_add_u32_e32 v1, v1, v7
	v_add_u32_e32 v1, v1, v8
	v_add_u32_e32 v1, v1, v9
	s_nop 0
	v_readfirstlane_b32 s101, v1
	s_getreg_b32 s5, hwreg(HW_REG_XCC_ID, 0, 4)
	s_lshl_b32 s5, s5, 8
	s_add_u32 s5, s5, 0x1000
	v_mov_b32_e32 v0, s5
	global_load_dword v1, v0, s[68:69] sc1
	s_waitcnt vmcnt(0)
	v_readfirstlane_b32 s98, v1
	s_nop 3
	s_sub_i32 s4, 1, s34
	s_getreg_b32 s5, hwreg(HW_REG_XCC_ID, 0, 4)
	s_mul_i32 s6, s98, s4
	s_lshl_b32 s5, s5, 8
	v_mov_b32_e32 v0, s5
	v_mov_b32_e32 v1, 1
	global_atomic_add v1, v0, v1, s[68:69] sc0
	s_mul_i32 s4, s101, s4
	v_mov_b32_e32 v0, 0
	s_waitcnt vmcnt(0)
	v_add_u32_e32 v1, 1, v1
	v_cmp_eq_u32_e32 vcc, s6, v1
	s_cbranch_vccz .Lgb_spin_s0
	buffer_wbl2 sc1
	s_waitcnt vmcnt(0)
	v_mov_b32_e32 v1, 1
	global_atomic_add v0, v1, s[14:15]

.LBB0_151:
	s_cmp_lt_i32 s35, 3
	s_cbranch_scc1 .LBB0_160
	v_mbcnt_lo_u32_b32 v0, -1, 0
	v_mbcnt_hi_u32_b32 v0, -1, v0
	s_waitcnt vmcnt(0) lgkmcnt(0)
	s_waitcnt vmcnt(0) lgkmcnt(0)
	v_add_u32_e32 v0, s84, v0
	v_cmp_gt_u32_e32 vcc, 64, v0
	s_barrier
	s_and_saveexec_b64 s[0:1], vcc
	s_cbranch_execz .LBB0_159
	s_waitcnt vmcnt(0)
	v_cmp_eq_u32_e32 vcc, 0, v0
	s_and_saveexec_b64 s[2:3], vcc
	s_cbranch_execz .LBB0_158
	s_sub_i32 s4, 2, s34
	s_getreg_b32 s5, hwreg(HW_REG_XCC_ID, 0, 4)
	s_mul_i32 s6, s98, s4
	s_lshl_b32 s5, s5, 8
	v_mov_b32_e32 v0, s5
	v_mov_b32_e32 v1, 1
	global_atomic_add v1, v0, v1, s[68:69] sc0
	s_mul_i32 s4, s101, s4
	v_mov_b32_e32 v0, 0
	s_waitcnt vmcnt(0)
	v_add_u32_e32 v1, 1, v1
	v_cmp_eq_u32_e32 vcc, s6, v1
	s_cbranch_vccz .Lgb_spin_s1
	buffer_wbl2 sc1
	s_waitcnt vmcnt(0)
	v_mov_b32_e32 v1, 1
	global_atomic_add v0, v1, s[14:15]

.LBB0_211:
	s_cmp_eq_u32 s100, 1
	s_cbranch_scc1 .Ldil_ret12
	s_cmp_lt_i32 s35, 4
	s_cbranch_scc1 .LBB0_220
	v_mbcnt_lo_u32_b32 v0, -1, 0
	v_mbcnt_hi_u32_b32 v0, -1, v0
	s_waitcnt vmcnt(0) lgkmcnt(0)
	s_waitcnt lgkmcnt(0)
	v_add_u32_e32 v0, s84, v0
	v_cmp_gt_u32_e32 vcc, 64, v0
	s_barrier
	s_and_saveexec_b64 s[0:1], vcc
	s_cbranch_execz .LBB0_219
	s_waitcnt vmcnt(0)
	s_waitcnt vmcnt(0)
	v_cmp_eq_u32_e32 vcc, 0, v0
	s_and_saveexec_b64 s[2:3], vcc
	s_cbranch_execz .LBB0_218
	s_sub_i32 s4, 3, s34
	s_getreg_b32 s5, hwreg(HW_REG_XCC_ID, 0, 4)
	s_mul_i32 s6, s98, s4
	s_lshl_b32 s5, s5, 8
	v_mov_b32_e32 v0, s5
	v_mov_b32_e32 v1, 1
	global_atomic_add v1, v0, v1, s[68:69] sc0
	s_mul_i32 s4, s101, s4
	v_mov_b32_e32 v0, 0
	s_waitcnt vmcnt(0)
	v_add_u32_e32 v1, 1, v1
	v_cmp_eq_u32_e32 vcc, s6, v1
	s_cbranch_vccz .Lgb_spin_s2
	buffer_wbl2 sc1
	s_waitcnt vmcnt(0)
	v_mov_b32_e32 v1, 1
	global_atomic_add v0, v1, s[14:15]

.LBB0_245:
	s_cmp_lt_i32 s35, 5
	s_cbranch_scc1 .LBB0_254
	v_mbcnt_lo_u32_b32 v0, -1, 0
	v_mbcnt_hi_u32_b32 v0, -1, v0
	s_waitcnt vmcnt(0) lgkmcnt(0)
	s_waitcnt vmcnt(0) lgkmcnt(0)
	v_add_u32_e32 v0, s84, v0
	v_cmp_gt_u32_e32 vcc, 64, v0
	s_barrier
	s_and_saveexec_b64 s[0:1], vcc
	s_cbranch_execz .LBB0_253
	s_waitcnt vmcnt(0)
	v_cmp_eq_u32_e32 vcc, 0, v0
	s_and_saveexec_b64 s[2:3], vcc
	s_cbranch_execz .LBB0_252
	s_sub_i32 s4, 4, s34
	s_getreg_b32 s5, hwreg(HW_REG_XCC_ID, 0, 4)
	s_mul_i32 s6, s98, s4
	s_lshl_b32 s5, s5, 8
	v_mov_b32_e32 v0, s5
	v_mov_b32_e32 v1, 1
	global_atomic_add v1, v0, v1, s[68:69] sc0
	s_mul_i32 s4, s101, s4
	v_mov_b32_e32 v0, 0
	s_waitcnt vmcnt(0)
	v_add_u32_e32 v1, 1, v1
	v_cmp_eq_u32_e32 vcc, s6, v1
	s_cbranch_vccz .Lgb_spin_s3
	buffer_wbl2 sc1
	s_waitcnt vmcnt(0)
	v_mov_b32_e32 v1, 1
	global_atomic_add v0, v1, s[14:15]

.LBB0_289:
	s_cmp_eq_u32 s99, 1
	s_cbranch_scc1 .Lmla_ret14
	s_cmp_lt_i32 s35, 6
	s_cbranch_scc1 .LBB0_298
	v_mbcnt_lo_u32_b32 v0, -1, 0
	v_mbcnt_hi_u32_b32 v0, -1, v0
	s_waitcnt vmcnt(0) lgkmcnt(0)
	s_waitcnt lgkmcnt(0)
	v_add_u32_e32 v0, s84, v0
	v_cmp_gt_u32_e32 vcc, 64, v0
	s_barrier
	s_and_saveexec_b64 s[0:1], vcc
	s_cbranch_execz .LBB0_297
	s_waitcnt vmcnt(0)
	s_waitcnt vmcnt(0)
	v_cmp_eq_u32_e32 vcc, 0, v0
	s_and_saveexec_b64 s[2:3], vcc
	s_cbranch_execz .LBB0_296
	s_sub_i32 s4, 5, s34
	s_getreg_b32 s5, hwreg(HW_REG_XCC_ID, 0, 4)
	s_mul_i32 s6, s98, s4
	s_lshl_b32 s5, s5, 8
	v_mov_b32_e32 v0, s5
	v_mov_b32_e32 v1, 1
	global_atomic_add v1, v0, v1, s[68:69] sc0
	s_mul_i32 s4, s101, s4
	v_mov_b32_e32 v0, 0
	s_waitcnt vmcnt(0)
	v_add_u32_e32 v1, 1, v1
	v_cmp_eq_u32_e32 vcc, s6, v1
	s_cbranch_vccz .Lgb_spin_s4
	buffer_wbl2 sc1
	s_waitcnt vmcnt(0)
	v_mov_b32_e32 v1, 1
	global_atomic_add v0, v1, s[14:15]

.LBB0_302:
	s_or_b64 exec, exec, s[2:3]
	s_cmp_lt_u32 s35, 7
	s_cbranch_scc1 .LBB0_311
	v_mbcnt_lo_u32_b32 v0, -1, 0
	v_mbcnt_hi_u32_b32 v0, -1, v0
	s_waitcnt vmcnt(0) lgkmcnt(0)
	s_waitcnt lgkmcnt(0)
	v_add_u32_e32 v0, s84, v0
	v_cmp_gt_u32_e32 vcc, 64, v0
	s_barrier
	s_and_saveexec_b64 s[0:1], vcc
	s_cbranch_execz .LBB0_310
	s_waitcnt vmcnt(0)
	s_waitcnt vmcnt(0)
	v_cmp_eq_u32_e32 vcc, 0, v0
	s_and_saveexec_b64 s[2:3], vcc
	s_cbranch_execz .LBB0_309
	s_sub_i32 s4, 6, s34
	s_getreg_b32 s5, hwreg(HW_REG_XCC_ID, 0, 4)
	s_mul_i32 s6, s98, s4
	s_lshl_b32 s5, s5, 8
	v_mov_b32_e32 v0, s5
	v_mov_b32_e32 v1, 1
	global_atomic_add v1, v0, v1, s[68:69] sc0
	s_mul_i32 s4, s101, s4
	v_mov_b32_e32 v0, 0
	s_waitcnt vmcnt(0)
	v_add_u32_e32 v1, 1, v1
	v_cmp_eq_u32_e32 vcc, s6, v1
	s_cbranch_vccz .Lgb_spin_s5
	buffer_wbl2 sc1
	s_waitcnt vmcnt(0)
	v_mov_b32_e32 v1, 1
	global_atomic_add v0, v1, s[14:15]

.LBB0_327:
	s_cmp_lt_i32 s35, 8
	s_cbranch_scc1 .LBB0_336
	v_mbcnt_lo_u32_b32 v0, -1, 0
	v_mbcnt_hi_u32_b32 v0, -1, v0
	s_waitcnt vmcnt(0) lgkmcnt(0)
	s_waitcnt vmcnt(0) lgkmcnt(0)
	v_add_u32_e32 v0, s84, v0
	v_cmp_gt_u32_e32 vcc, 64, v0
	s_barrier
	s_and_saveexec_b64 s[0:1], vcc
	s_cbranch_execz .LBB0_335
	s_waitcnt vmcnt(0)
	v_cmp_eq_u32_e32 vcc, 0, v0
	s_and_saveexec_b64 s[2:3], vcc
	s_cbranch_execz .LBB0_334
	s_sub_i32 s4, 7, s34
	s_getreg_b32 s5, hwreg(HW_REG_XCC_ID, 0, 4)
	s_mul_i32 s6, s98, s4
	s_lshl_b32 s5, s5, 8
	v_mov_b32_e32 v0, s5
	v_mov_b32_e32 v1, 1
	global_atomic_add v1, v0, v1, s[68:69] sc0
	s_mul_i32 s4, s101, s4
	v_mov_b32_e32 v0, 0
	s_waitcnt vmcnt(0)
	v_add_u32_e32 v1, 1, v1
	v_cmp_eq_u32_e32 vcc, s6, v1
	s_cbranch_vccz .Lgb_spin_s6
	buffer_wbl2 sc1
	s_waitcnt vmcnt(0)
	v_mov_b32_e32 v1, 1
	global_atomic_add v0, v1, s[14:15]

.LBB0_348:
	s_or_b64 exec, exec, s[2:3]
	s_cmp_lt_i32 s35, 9
	s_cbranch_scc1 .LBB0_357
	v_mbcnt_lo_u32_b32 v0, -1, 0
	v_mbcnt_hi_u32_b32 v0, -1, v0
	s_waitcnt vmcnt(0) lgkmcnt(0)
	s_waitcnt lgkmcnt(0)
	v_add_u32_e32 v0, s84, v0
	v_cmp_gt_u32_e32 vcc, 64, v0
	s_barrier
	s_and_saveexec_b64 s[0:1], vcc
	s_cbranch_execz .LBB0_356
	s_waitcnt vmcnt(0)
	s_waitcnt vmcnt(0)
	v_cmp_eq_u32_e32 vcc, 0, v0
	s_and_saveexec_b64 s[2:3], vcc
	s_cbranch_execz .LBB0_355
	s_sub_i32 s4, 8, s34
	s_getreg_b32 s5, hwreg(HW_REG_XCC_ID, 0, 4)
	s_mul_i32 s6, s98, s4
	s_lshl_b32 s5, s5, 8
	v_mov_b32_e32 v0, s5
	v_mov_b32_e32 v1, 1
	global_atomic_add v1, v0, v1, s[68:69] sc0
	s_mul_i32 s4, s101, s4
	v_mov_b32_e32 v0, 0
	s_waitcnt vmcnt(0)
	v_add_u32_e32 v1, 1, v1
	v_cmp_eq_u32_e32 vcc, s6, v1
	s_cbranch_vccz .Lgb_spin_s7
	buffer_wbl2 sc1
	s_waitcnt vmcnt(0)
	v_mov_b32_e32 v1, 1
	global_atomic_add v0, v1, s[14:15]

.LBB0_373:
	s_cmp_lt_i32 s35, 10
	s_cbranch_scc1 .LBB0_382
	v_mbcnt_lo_u32_b32 v0, -1, 0
	v_mbcnt_hi_u32_b32 v0, -1, v0
	s_waitcnt vmcnt(0) lgkmcnt(0)
	s_waitcnt vmcnt(0) lgkmcnt(0)
	v_add_u32_e32 v0, s84, v0
	v_cmp_gt_u32_e32 vcc, 64, v0
	s_barrier
	s_and_saveexec_b64 s[0:1], vcc
	s_cbranch_execz .LBB0_381
	s_waitcnt vmcnt(0)
	v_cmp_eq_u32_e32 vcc, 0, v0
	s_and_saveexec_b64 s[2:3], vcc
	s_cbranch_execz .LBB0_380
	s_sub_i32 s4, 9, s34
	s_getreg_b32 s5, hwreg(HW_REG_XCC_ID, 0, 4)
	s_mul_i32 s6, s98, s4
	s_lshl_b32 s5, s5, 8
	v_mov_b32_e32 v0, s5
	v_mov_b32_e32 v1, 1
	global_atomic_add v1, v0, v1, s[68:69] sc0
	s_mul_i32 s4, s101, s4
	v_mov_b32_e32 v0, 0
	s_waitcnt vmcnt(0)
	v_add_u32_e32 v1, 1, v1
	v_cmp_eq_u32_e32 vcc, s6, v1
	s_cbranch_vccz .Lgb_spin_s8
	buffer_wbl2 sc1
	s_waitcnt vmcnt(0)
	v_mov_b32_e32 v1, 1
	global_atomic_add v0, v1, s[14:15]

.LBB0_398:
	s_cmp_lt_i32 s35, 11
	s_cbranch_scc1 .LBB0_407
	v_mbcnt_lo_u32_b32 v0, -1, 0
	v_mbcnt_hi_u32_b32 v0, -1, v0
	s_waitcnt vmcnt(0) lgkmcnt(0)
	s_waitcnt vmcnt(0) lgkmcnt(0)
	v_add_u32_e32 v0, s84, v0
	v_cmp_gt_u32_e32 vcc, 64, v0
	s_barrier
	s_and_saveexec_b64 s[0:1], vcc
	s_cbranch_execz .LBB0_406
	s_waitcnt vmcnt(0)
	v_cmp_eq_u32_e32 vcc, 0, v0
	s_and_saveexec_b64 s[2:3], vcc
	s_cbranch_execz .LBB0_405
	s_sub_i32 s4, 10, s34
	s_getreg_b32 s5, hwreg(HW_REG_XCC_ID, 0, 4)
	s_mul_i32 s6, s98, s4
	s_lshl_b32 s5, s5, 8
	v_mov_b32_e32 v0, s5
	v_mov_b32_e32 v1, 1
	global_atomic_add v1, v0, v1, s[68:69] sc0
	s_mul_i32 s4, s101, s4
	v_mov_b32_e32 v0, 0
	s_waitcnt vmcnt(0)
	v_add_u32_e32 v1, 1, v1
	v_cmp_eq_u32_e32 vcc, s6, v1
	s_cbranch_vccz .Lgb_spin_s9
	buffer_wbl2 sc1
	s_waitcnt vmcnt(0)
	v_mov_b32_e32 v1, 1
	global_atomic_add v0, v1, s[14:15]

.LBB0_442:
	s_or_b64 exec, exec, s[0:1]
	s_cmp_lt_i32 s35, 12
	s_cbranch_scc1 .LBB0_451
	v_mbcnt_lo_u32_b32 v0, -1, 0
	v_mbcnt_hi_u32_b32 v0, -1, v0
	s_waitcnt vmcnt(0) lgkmcnt(0)
	s_waitcnt lgkmcnt(0)
	v_add_u32_e32 v0, s84, v0
	v_cmp_gt_u32_e32 vcc, 64, v0
	s_barrier
	s_and_saveexec_b64 s[0:1], vcc
	s_cbranch_execz .LBB0_450
	s_waitcnt vmcnt(0)
	s_waitcnt vmcnt(0)
	v_cmp_eq_u32_e32 vcc, 0, v0
	s_and_saveexec_b64 s[2:3], vcc
	s_cbranch_execz .LBB0_449
	s_sub_i32 s4, 11, s34
	s_getreg_b32 s5, hwreg(HW_REG_XCC_ID, 0, 4)
	s_mul_i32 s6, s98, s4
	s_lshl_b32 s5, s5, 8
	v_mov_b32_e32 v0, s5
	v_mov_b32_e32 v1, 1
	global_atomic_add v1, v0, v1, s[68:69] sc0
	s_mul_i32 s4, s101, s4
	v_mov_b32_e32 v0, 0
	s_waitcnt vmcnt(0)
	v_add_u32_e32 v1, 1, v1
	v_cmp_eq_u32_e32 vcc, s6, v1
	s_cbranch_vccz .Lgb_spin_s10
	buffer_wbl2 sc1
	s_waitcnt vmcnt(0)
	v_mov_b32_e32 v1, 1
	global_atomic_add v0, v1, s[14:15]

.LBB0_531:
	s_cmp_lt_i32 s35, 13
	s_cbranch_scc1 .LBB0_540
	v_mbcnt_lo_u32_b32 v0, -1, 0
	v_mbcnt_hi_u32_b32 v0, -1, v0
	s_waitcnt vmcnt(0) lgkmcnt(0)
	s_waitcnt vmcnt(0) lgkmcnt(0)
	v_add_u32_e32 v0, s84, v0
	v_cmp_gt_u32_e32 vcc, 64, v0
	s_barrier
	s_and_saveexec_b64 s[0:1], vcc
	s_cbranch_execz .LBB0_539
	s_waitcnt vmcnt(0)
	v_cmp_eq_u32_e32 vcc, 0, v0
	s_and_saveexec_b64 s[2:3], vcc
	s_cbranch_execz .LBB0_538
	s_sub_i32 s4, 12, s34
	s_getreg_b32 s5, hwreg(HW_REG_XCC_ID, 0, 4)
	s_mul_i32 s6, s98, s4
	s_lshl_b32 s5, s5, 8
	v_mov_b32_e32 v0, s5
	v_mov_b32_e32 v1, 1
	global_atomic_add v1, v0, v1, s[68:69] sc0
	s_mul_i32 s4, s101, s4
	v_mov_b32_e32 v0, 0
	s_waitcnt vmcnt(0)
	v_add_u32_e32 v1, 1, v1
	v_cmp_eq_u32_e32 vcc, s6, v1
	s_cbranch_vccz .Lgb_spin_s11
	buffer_wbl2 sc1
	s_waitcnt vmcnt(0)
	v_mov_b32_e32 v1, 1
	global_atomic_add v0, v1, s[14:15]

.Ldil_ret12:
.LBB0_590:
	s_cmp_lt_i32 s35, 14
	s_cbranch_scc1 .LBB0_599
	v_mbcnt_lo_u32_b32 v0, -1, 0
	v_mbcnt_hi_u32_b32 v0, -1, v0
	s_waitcnt vmcnt(0) lgkmcnt(0)
	s_waitcnt lgkmcnt(0)
	v_add_u32_e32 v0, s84, v0
	v_cmp_gt_u32_e32 vcc, 64, v0
	s_barrier
	s_and_saveexec_b64 s[0:1], vcc
	s_cbranch_execz .LBB0_598
	s_waitcnt vmcnt(0)
	s_waitcnt vmcnt(0)
	v_cmp_eq_u32_e32 vcc, 0, v0
	s_and_saveexec_b64 s[2:3], vcc
	s_cbranch_execz .LBB0_597
	s_sub_i32 s4, 13, s34
	s_getreg_b32 s5, hwreg(HW_REG_XCC_ID, 0, 4)
	s_mul_i32 s6, s98, s4
	s_lshl_b32 s5, s5, 8
	v_mov_b32_e32 v0, s5
	v_mov_b32_e32 v1, 1
	global_atomic_add v1, v0, v1, s[68:69] sc0
	s_mul_i32 s4, s101, s4
	v_mov_b32_e32 v0, 0
	s_waitcnt vmcnt(0)
	v_add_u32_e32 v1, 1, v1
	v_cmp_eq_u32_e32 vcc, s6, v1
	s_cbranch_vccz .Lgb_spin_s12
	buffer_wbl2 sc1
	s_waitcnt vmcnt(0)
	v_mov_b32_e32 v1, 1
	global_atomic_add v0, v1, s[14:15]

.LBB0_624:
	s_cmp_lt_i32 s35, 15
	s_cbranch_scc1 .LBB0_633
	v_mbcnt_lo_u32_b32 v0, -1, 0
	v_mbcnt_hi_u32_b32 v0, -1, v0
	s_waitcnt vmcnt(0) lgkmcnt(0)
	s_waitcnt vmcnt(0) lgkmcnt(0)
	v_add_u32_e32 v0, s84, v0
	v_cmp_gt_u32_e32 vcc, 64, v0
	s_barrier
	s_and_saveexec_b64 s[0:1], vcc
	s_cbranch_execz .LBB0_632
	s_waitcnt vmcnt(0)
	v_cmp_eq_u32_e32 vcc, 0, v0
	s_and_saveexec_b64 s[2:3], vcc
	s_cbranch_execz .LBB0_631
	s_sub_i32 s4, 14, s34
	s_getreg_b32 s5, hwreg(HW_REG_XCC_ID, 0, 4)
	s_mul_i32 s6, s98, s4
	s_lshl_b32 s5, s5, 8
	v_mov_b32_e32 v0, s5
	v_mov_b32_e32 v1, 1
	global_atomic_add v1, v0, v1, s[68:69] sc0
	s_mul_i32 s4, s101, s4
	v_mov_b32_e32 v0, 0
	s_waitcnt vmcnt(0)
	v_add_u32_e32 v1, 1, v1
	v_cmp_eq_u32_e32 vcc, s6, v1
	s_cbranch_vccz .Lgb_spin_s13
	buffer_wbl2 sc1
	s_waitcnt vmcnt(0)
	v_mov_b32_e32 v1, 1
	global_atomic_add v0, v1, s[14:15]

.Lmla_ret14:
.LBB0_668:
	s_cmp_lt_i32 s35, 16
	s_cbranch_scc1 .LBB0_677
	v_mbcnt_lo_u32_b32 v0, -1, 0
	v_mbcnt_hi_u32_b32 v0, -1, v0
	s_waitcnt vmcnt(0) lgkmcnt(0)
	s_waitcnt lgkmcnt(0)
	v_add_u32_e32 v0, s84, v0
	v_cmp_gt_u32_e32 vcc, 64, v0
	s_barrier
	s_and_saveexec_b64 s[0:1], vcc
	s_cbranch_execz .LBB0_676
	s_waitcnt vmcnt(0)
	s_waitcnt vmcnt(0)
	v_cmp_eq_u32_e32 vcc, 0, v0
	s_and_saveexec_b64 s[2:3], vcc
	s_cbranch_execz .LBB0_675
	s_sub_i32 s4, 15, s34
	s_getreg_b32 s5, hwreg(HW_REG_XCC_ID, 0, 4)
	s_mul_i32 s6, s98, s4
	s_lshl_b32 s5, s5, 8
	v_mov_b32_e32 v0, s5
	v_mov_b32_e32 v1, 1
	global_atomic_add v1, v0, v1, s[68:69] sc0
	s_mul_i32 s4, s101, s4
	v_mov_b32_e32 v0, 0
	s_waitcnt vmcnt(0)
	v_add_u32_e32 v1, 1, v1
	v_cmp_eq_u32_e32 vcc, s6, v1
	s_cbranch_vccz .Lgb_spin_s14
	buffer_wbl2 sc1
	s_waitcnt vmcnt(0)
	v_mov_b32_e32 v1, 1
	global_atomic_add v0, v1, s[14:15]

.LBB0_681:
	s_or_b64 exec, exec, s[2:3]
	s_cmp_lt_u32 s35, 17
	s_cbranch_scc1 .LBB0_690
	v_mbcnt_lo_u32_b32 v0, -1, 0
	v_mbcnt_hi_u32_b32 v0, -1, v0
	s_waitcnt vmcnt(0) lgkmcnt(0)
	s_waitcnt lgkmcnt(0)
	v_add_u32_e32 v0, s84, v0
	v_cmp_gt_u32_e32 vcc, 64, v0
	s_barrier
	s_and_saveexec_b64 s[0:1], vcc
	s_cbranch_execz .LBB0_689
	s_waitcnt vmcnt(0)
	s_waitcnt vmcnt(0)
	v_cmp_eq_u32_e32 vcc, 0, v0
	s_and_saveexec_b64 s[2:3], vcc
	s_cbranch_execz .LBB0_688
	s_sub_i32 s4, 16, s34
	s_getreg_b32 s5, hwreg(HW_REG_XCC_ID, 0, 4)
	s_mul_i32 s6, s98, s4
	s_lshl_b32 s5, s5, 8
	v_mov_b32_e32 v0, s5
	v_mov_b32_e32 v1, 1
	global_atomic_add v1, v0, v1, s[68:69] sc0
	s_mul_i32 s4, s101, s4
	v_mov_b32_e32 v0, 0
	s_waitcnt vmcnt(0)
	v_add_u32_e32 v1, 1, v1
	v_cmp_eq_u32_e32 vcc, s6, v1
	s_cbranch_vccz .Lgb_spin_s15
	buffer_wbl2 sc1
	s_waitcnt vmcnt(0)
	v_mov_b32_e32 v1, 1
	global_atomic_add v0, v1, s[14:15]

.LBB0_706:
	s_cmp_lt_i32 s35, 18
	s_cbranch_scc1 .LBB0_715
	v_mbcnt_lo_u32_b32 v0, -1, 0
	v_mbcnt_hi_u32_b32 v0, -1, v0
	s_waitcnt vmcnt(0) lgkmcnt(0)
	s_waitcnt vmcnt(0) lgkmcnt(0)
	v_add_u32_e32 v0, s84, v0
	v_cmp_gt_u32_e32 vcc, 64, v0
	s_barrier
	s_and_saveexec_b64 s[0:1], vcc
	s_cbranch_execz .LBB0_714
	s_waitcnt vmcnt(0)
	v_cmp_eq_u32_e32 vcc, 0, v0
	s_and_saveexec_b64 s[2:3], vcc
	s_cbranch_execz .LBB0_713
	s_sub_i32 s4, 17, s34
	s_getreg_b32 s5, hwreg(HW_REG_XCC_ID, 0, 4)
	s_mul_i32 s6, s98, s4
	s_lshl_b32 s5, s5, 8
	v_mov_b32_e32 v0, s5
	v_mov_b32_e32 v1, 1
	global_atomic_add v1, v0, v1, s[68:69] sc0
	s_mul_i32 s4, s101, s4
	v_mov_b32_e32 v0, 0
	s_waitcnt vmcnt(0)
	v_add_u32_e32 v1, 1, v1
	v_cmp_eq_u32_e32 vcc, s6, v1
	s_cbranch_vccz .Lgb_spin_s16
	buffer_wbl2 sc1
	s_waitcnt vmcnt(0)
	v_mov_b32_e32 v1, 1
	global_atomic_add v0, v1, s[14:15]

.LBB0_719:
	s_or_b64 exec, exec, s[0:1]
	s_cmp_lt_u32 s35, 19
	s_cbranch_scc1 .LBB0_728
	v_mbcnt_lo_u32_b32 v0, -1, 0
	v_mbcnt_hi_u32_b32 v0, -1, v0
	s_waitcnt vmcnt(0) lgkmcnt(0)
	s_nop 0
	v_add_u32_e32 v0, s84, v0
	v_cmp_gt_u32_e32 vcc, 64, v0
	s_barrier
	s_and_saveexec_b64 s[0:1], vcc
	s_cbranch_execz .LBB0_727
	s_waitcnt vmcnt(0)
	s_waitcnt vmcnt(0)
	v_cmp_eq_u32_e32 vcc, 0, v0
	s_and_saveexec_b64 s[2:3], vcc
	s_cbranch_execz .LBB0_726
	s_sub_i32 s4, 18, s34
	s_getreg_b32 s5, hwreg(HW_REG_XCC_ID, 0, 4)
	s_mul_i32 s6, s98, s4
	s_lshl_b32 s5, s5, 8
	v_mov_b32_e32 v0, s5
	v_mov_b32_e32 v1, 1
	global_atomic_add v1, v0, v1, s[68:69] sc0
	s_mul_i32 s4, s101, s4
	v_mov_b32_e32 v0, 0
	s_waitcnt vmcnt(0)
	v_add_u32_e32 v1, 1, v1
	v_cmp_eq_u32_e32 vcc, s6, v1
	s_cbranch_vccz .Lgb_spin_s17
	buffer_wbl2 sc1
	s_waitcnt vmcnt(0)
	v_mov_b32_e32 v1, 1
	global_atomic_add v0, v1, s[14:15]

.LBB0_744:
	s_cmp_lt_i32 s35, 20
	s_cbranch_scc1 .LBB0_753
	v_mbcnt_lo_u32_b32 v0, -1, 0
	v_mbcnt_hi_u32_b32 v0, -1, v0
	s_waitcnt vmcnt(0) lgkmcnt(0)
	s_waitcnt vmcnt(0) lgkmcnt(0)
	v_add_u32_e32 v0, s84, v0
	v_cmp_gt_u32_e32 vcc, 64, v0
	s_barrier
	s_and_saveexec_b64 s[0:1], vcc
	s_cbranch_execz .LBB0_752
	s_waitcnt vmcnt(0)
	v_cmp_eq_u32_e32 vcc, 0, v0
	s_and_saveexec_b64 s[2:3], vcc
	s_cbranch_execz .LBB0_751
	s_sub_i32 s4, 19, s34
	s_getreg_b32 s5, hwreg(HW_REG_XCC_ID, 0, 4)
	s_mul_i32 s6, s98, s4
	s_lshl_b32 s5, s5, 8
	v_mov_b32_e32 v0, s5
	v_mov_b32_e32 v1, 1
	global_atomic_add v1, v0, v1, s[68:69] sc0
	s_mul_i32 s4, s101, s4
	v_mov_b32_e32 v0, 0
	s_waitcnt vmcnt(0)
	v_add_u32_e32 v1, 1, v1
	v_cmp_eq_u32_e32 vcc, s6, v1
	s_cbranch_vccz .Lgb_spin_s18
	buffer_wbl2 sc1
	s_waitcnt vmcnt(0)
	v_mov_b32_e32 v1, 1
	global_atomic_add v0, v1, s[14:15]

.LBB0_769:
	s_cmp_lt_i32 s35, 21
	s_cbranch_scc1 .LBB0_778
	v_mbcnt_lo_u32_b32 v0, -1, 0
	v_mbcnt_hi_u32_b32 v0, -1, v0
	s_waitcnt vmcnt(0) lgkmcnt(0)
	s_waitcnt vmcnt(0) lgkmcnt(0)
	v_add_u32_e32 v0, s84, v0
	v_cmp_gt_u32_e32 vcc, 64, v0
	s_barrier
	s_and_saveexec_b64 s[0:1], vcc
	s_cbranch_execz .LBB0_777
	s_waitcnt vmcnt(0)
	v_cmp_eq_u32_e32 vcc, 0, v0
	s_and_saveexec_b64 s[2:3], vcc
	s_cbranch_execz .LBB0_776
	s_sub_i32 s4, 20, s34
	s_getreg_b32 s5, hwreg(HW_REG_XCC_ID, 0, 4)
	s_mul_i32 s6, s98, s4
	s_lshl_b32 s5, s5, 8
	v_mov_b32_e32 v0, s5
	v_mov_b32_e32 v1, 1
	global_atomic_add v1, v0, v1, s[68:69] sc0
	s_mul_i32 s4, s101, s4
	v_mov_b32_e32 v0, 0
	s_waitcnt vmcnt(0)
	v_add_u32_e32 v1, 1, v1
	v_cmp_eq_u32_e32 vcc, s6, v1
	s_cbranch_vccz .Lgb_spin_s19
	buffer_wbl2 sc1
	s_waitcnt vmcnt(0)
	v_mov_b32_e32 v1, 1
	global_atomic_add v0, v1, s[14:15]

.LBB0_782:
	s_or_b64 exec, exec, s[0:1]
	s_cmp_lt_u32 s35, 22
	s_cbranch_scc1 .LBB0_791
	v_mbcnt_lo_u32_b32 v0, -1, 0
	v_mbcnt_hi_u32_b32 v0, -1, v0
	s_waitcnt vmcnt(0) lgkmcnt(0)
	s_waitcnt lgkmcnt(0)
	v_add_u32_e32 v0, s84, v0
	v_cmp_gt_u32_e32 vcc, 64, v0
	s_barrier
	s_and_saveexec_b64 s[0:1], vcc
	s_cbranch_execz .LBB0_790
	s_waitcnt vmcnt(0)
	s_waitcnt vmcnt(0)
	v_cmp_eq_u32_e32 vcc, 0, v0
	s_and_saveexec_b64 s[2:3], vcc
	s_cbranch_execz .LBB0_789
	s_sub_i32 s4, 21, s34
	s_getreg_b32 s5, hwreg(HW_REG_XCC_ID, 0, 4)
	s_mul_i32 s6, s98, s4
	s_lshl_b32 s5, s5, 8
	v_mov_b32_e32 v0, s5
	v_mov_b32_e32 v1, 1
	global_atomic_add v1, v0, v1, s[68:69] sc0
	s_mul_i32 s4, s101, s4
	v_mov_b32_e32 v0, 0
	s_waitcnt vmcnt(0)
	v_add_u32_e32 v1, 1, v1
	v_cmp_eq_u32_e32 vcc, s6, v1
	s_cbranch_vccz .Lgb_spin_s20
	buffer_wbl2 sc1
	s_waitcnt vmcnt(0)
	v_mov_b32_e32 v1, 1
	global_atomic_add v0, v1, s[14:15]
